# attention: row-max chain split into two independent max3 chains (shorter dependent VALU chain in the P.V gaps)
# baseline (speedup 1.0000x reference)
; __device__ __forceinline__ void partialSM(f32x16& p0, f32x16& p1, float& m_reg, float& mn, float& alpha) {
;     constexpr float C = SCALE * 1.4426950408889634f;
;     float pmax = p0[0];
; #pragma unroll
;     for (int r = 1; r < 16; ++r) pmax = fmaxf(pmax, p0[r]);
; #pragma unroll
;     for (int r = 0; r < 16; ++r) pmax = fmaxf(pmax, p1[r]);
;     { auto rr = __builtin_amdgcn_permlane32_swap(__float_as_uint(pmax), __float_as_uint(pmax), false, false);
;       pmax = fmaxf(__uint_as_float(rr[0]), __uint_as_float(rr[1])); }
; __device__ __forceinline__ void finishSM(f32x16& p0, f32x16& p1, float alpha, float& l_reg, bf16x8& pa0, bf16x8& pa1, bf16x8& pa2, bf16x8& pa3) {
; #pragma unroll
;     for (int r = 0; r < 16; ++r) p1[r] = __builtin_amdgcn_exp2f(p1[r]);
;     float ps = 0;
; #pragma unroll
;     for (int r = 0; r < 16; ++r) ps += p0[r];
; #pragma unroll
;     for (int r = 0; r < 16; ++r) ps += p1[r];
;     { auto rr = __builtin_amdgcn_permlane32_swap(__float_as_uint(ps), __float_as_uint(ps), false, false);
;       ps = __uint_as_float(rr[0]) + __uint_as_float(rr[1]); }
;     l_reg = l_reg * alpha + ps;
;     ...
;     PK4(p0, 0, pa0); PK4(p0, 8, pa1); PK4(p1, 0, pa2); PK4(p1, 8, pa3);
;     ...
; }
; __device__ __forceinline__ void qkt(f32x16& p0, f32x16& p1, const char* Ks, const bf16x8* qr, int r32, int hi, int comp) {
;     p0 = f32x16{}; p1 = f32x16{};
; #pragma unroll
;     for (int d0 = 0; d0 < 4; ++d0) { const int cb = (comp * 64 + d0 * 16 + hi * 8) * 2;
;         const bf16x8 b0 = *reinterpret_cast<const bf16x8*>(Ks + KSWZ(r32, cb));
;         const bf16x8 b1 = *reinterpret_cast<const bf16x8*>(Ks + KSWZ(32 + r32, cb));
;         p0 = __builtin_amdgcn_mfma_f32_32x32x16_bf16(b0, qr[d0], p0, 0, 0, 0);
;         p1 = __builtin_amdgcn_mfma_f32_32x32x16_bf16(b1, qr[d0], p1, 0, 0, 0); }
; }
; __device__ __forceinline__ int v_st(int k, int c) { const int kk = (k & ~0xC) | ((k & 4) << 1) | ((k & 8) >> 1); return ((kk >> 3) * 4 + (c >> 5)) * 512 + ((kk & 7) * 32 + (c & 31)) * 2; }
; __device__ __forceinline__ int v_rd_base(int lane) { return ((lane & 3) << 3) | (((lane >> 2) & 3) << 6) | (((lane >> 4) & 1) << 5) | (((lane >> 5) & 1) << 8); }
; template <int OFF> __device__ __forceinline__ s16x4 tr_read(int vb) {
;     s16x4 r; asm volatile("ds_read_b64_tr_b16 %0, %1 offset:%2" : "=&v"(r) : "v"(vb), "i"(OFF) : "memory"); return r;
; }
.LBB0_262:
	ds_read_b128 v[64:67], v170 offset:49152
	ds_read_b128 v[68:71], v170 offset:57344
	v_add_f32_e32 v177, 0, v240
	v_add_f32_e32 v177, v241, v177
	v_add_f32_e32 v177, v242, v177
	s_waitcnt lgkmcnt(1)
	v_mfma_f32_32x32x16_bf16 v[80:95], v[64:67], v[110:113], 0
	v_add_f32_e32 v177, v243, v177
	v_add_f32_e32 v177, v244, v177
	ds_read_b128 v[178:181], v171 offset:49152
	ds_read_b128 v[220:223], v171 offset:57344
	v_add_f32_e32 v177, v245, v177
	v_add_f32_e32 v177, v246, v177
	v_add_f32_e32 v177, v247, v177
	v_add_f32_e32 v177, v248, v177
	s_waitcnt lgkmcnt(2)
	v_mfma_f32_32x32x16_bf16 v[64:79], v[68:71], v[110:113], 0
	v_add_f32_e32 v177, v249, v177
	v_add_f32_e32 v177, v250, v177
	v_add_f32_e32 v177, v251, v177
	v_exp_f32_e32 v128, v128
	v_add_f32_e32 v177, v206, v177
	v_exp_f32_e32 v129, v129
	v_add_f32_e32 v177, v207, v177
	s_waitcnt lgkmcnt(1)
	v_mfma_f32_32x32x16_bf16 v[80:95], v[178:181], v[106:109], v[80:95]
	v_exp_f32_e32 v126, v126
	v_add_f32_e32 v177, v208, v177
	v_exp_f32_e32 v127, v127
	v_add_f32_e32 v177, v209, v177
	v_exp_f32_e32 v122, v122
	v_add_f32_e32 v177, v128, v177
	v_exp_f32_e32 v123, v123
	s_waitcnt lgkmcnt(0)
	v_mfma_f32_32x32x16_bf16 v[64:79], v[220:223], v[106:109], v[64:79]
	ds_read_b128 v[178:181], v173 offset:49152
	ds_read_b128 v[220:223], v173 offset:57344
	v_add_f32_e32 v177, v129, v177
	v_exp_f32_e32 v118, v118
	v_add_f32_e32 v177, v126, v177
	v_exp_f32_e32 v119, v119
	v_add_f32_e32 v177, v127, v177
	v_exp_f32_e32 v116, v116
	s_waitcnt lgkmcnt(1)
	v_mfma_f32_32x32x16_bf16 v[80:95], v[178:181], v[102:105], v[80:95]
	v_add_f32_e32 v177, v122, v177
	v_exp_f32_e32 v117, v117
	v_add_f32_e32 v177, v123, v177
	v_exp_f32_e32 v124, v124
	v_add_f32_e32 v177, v118, v177
	v_exp_f32_e32 v125, v125
	v_add_f32_e32 v177, v119, v177
	s_waitcnt lgkmcnt(0)
	v_mfma_f32_32x32x16_bf16 v[64:79], v[220:223], v[102:105], v[64:79]
	ds_read_b128 v[178:181], v172 offset:49152
	ds_read_b128 v[220:223], v172 offset:57344
	v_exp_f32_e32 v120, v120
	v_add_f32_e32 v177, v116, v177
	v_exp_f32_e32 v121, v121
	v_add_f32_e32 v177, v117, v177
	v_exp_f32_e32 v114, v114
	v_add_f32_e32 v177, v124, v177
	s_waitcnt lgkmcnt(1)
	v_mfma_f32_32x32x16_bf16 v[80:95], v[178:181], v[98:101], v[80:95]
	v_exp_f32_e32 v115, v115
	v_add_f32_e32 v177, v125, v177
	v_add_f32_e32 v177, v120, v177
	v_add_f32_e32 v177, v121, v177
	v_add_f32_e32 v177, v114, v177
	v_add_f32_e32 v177, v115, v177
	v_mov_b32_e32 v178, v177
	s_waitcnt lgkmcnt(0)
	v_mfma_f32_32x32x16_bf16 v[64:79], v[220:223], v[98:101], v[64:79]
	v_cvt_pk_bf16_f32 v212, v240, v241
	v_cvt_pk_bf16_f32 v213, v242, v243
	v_cvt_pk_bf16_f32 v214, v244, v245
	v_cvt_pk_bf16_f32 v215, v246, v247
	v_cvt_pk_bf16_f32 v180, v248, v249
	v_cvt_pk_bf16_f32 v181, v250, v251
	v_cvt_pk_bf16_f32 v182, v206, v207
	v_permlane32_swap_b32_e32 v177, v178
	v_cvt_pk_bf16_f32 v183, v208, v209
	v_permlane32_swap_b32_e32 v180, v182
	v_cvt_pk_bf16_f32 v184, v128, v129
	v_cvt_pk_bf16_f32 v185, v126, v127
	v_cvt_pk_bf16_f32 v186, v122, v123
	v_cvt_pk_bf16_f32 v187, v118, v119
	v_cvt_pk_bf16_f32 v216, v116, v117
	v_cvt_pk_bf16_f32 v217, v124, v125
	v_cvt_pk_bf16_f32 v218, v120, v121
	v_cvt_pk_bf16_f32 v219, v114, v115
	v_permlane32_swap_b32_e32 v212, v214
	v_permlane32_swap_b32_e32 v213, v215
	v_permlane32_swap_b32_e32 v181, v183
	v_permlane32_swap_b32_e32 v184, v186
	v_permlane32_swap_b32_e32 v185, v187
	v_permlane32_swap_b32_e32 v216, v218
	v_permlane32_swap_b32_e32 v217, v219
	v_add_u32_e32 v122, 0x10000, v176
	global_load_dwordx4 v[240:243], v176, s[58:59]
	global_load_dwordx4 v[244:247], v176, s[28:29]
	global_load_dwordx4 v[206:209], v122, s[58:59]
	s_nop 0
	global_load_dwordx4 v[248:251], v122, s[28:29]
	ds_read_b64_tr_b16 v[220:221], v160 offset:0
	ds_read_b64_tr_b16 v[222:223], v160 offset:0x800
	ds_read_b64_tr_b16 v[224:225], v160 offset:0x1000
	ds_read_b64_tr_b16 v[226:227], v160 offset:0x1800
	ds_read_b64_tr_b16 v[228:229], v160 offset:0x2000
	ds_read_b64_tr_b16 v[230:231], v160 offset:0x2800
	ds_read_b64_tr_b16 v[232:233], v160 offset:0x3000
	ds_read_b64_tr_b16 v[234:235], v160 offset:0x3800
	s_waitcnt lgkmcnt(0)
	s_nop 0
	v_mfma_f32_32x32x16_bf16 v[48:63], v[212:215], v[220:223], v[48:63]
	ds_read_b64_tr_b16 v[220:221], v160 offset:0x200
	ds_read_b64_tr_b16 v[222:223], v160 offset:0xa00
	v_max_f32_e32 v179, v81, v81
	v_max_f32_e32 v255, v80, v80
	v_max3_f32 v210, v64, v65, v66
	v_max_f32_e32 v179, v255, v179
	v_max3_f32 v210, v210, v67, v68
	v_mfma_f32_32x32x16_bf16 v[48:63], v[180:183], v[224:227], v[48:63]
	ds_read_b64_tr_b16 v[224:225], v160 offset:0x1200
	ds_read_b64_tr_b16 v[226:227], v160 offset:0x1a00
	v_max3_f32 v179, v179, v82, v83
	v_max3_f32 v210, v210, v69, v70
	v_max3_f32 v179, v179, v84, v85
	v_max3_f32 v210, v210, v71, v72
	v_max3_f32 v179, v179, v86, v87
	v_mfma_f32_32x32x16_bf16 v[48:63], v[184:187], v[228:231], v[48:63]
	ds_read_b64_tr_b16 v[228:229], v160 offset:0x2200
	ds_read_b64_tr_b16 v[230:231], v160 offset:0x2a00
	v_max3_f32 v210, v210, v73, v74
	v_max3_f32 v179, v179, v88, v89
	v_max3_f32 v210, v210, v75, v76
	v_max3_f32 v179, v179, v90, v91
	v_max3_f32 v210, v210, v77, v78
	v_mfma_f32_32x32x16_bf16 v[48:63], v[216:219], v[232:235], v[48:63]
	ds_read_b64_tr_b16 v[232:233], v160 offset:0x3200
	ds_read_b64_tr_b16 v[234:235], v160 offset:0x3a00
	v_max3_f32 v179, v179, v92, v93
	v_max_f32_e32 v210, v79, v210
	v_max3_f32 v179, v179, v94, v95
	v_max_f32_e32 v179, v179, v210
	v_mov_b32_e32 v255, v179
	s_nop 1
	v_permlane32_swap_b32_e32 v179, v255
	s_waitcnt lgkmcnt(0)
; #define SBAR() __builtin_amdgcn_sched_barrier(0)
; #define SWRITE(b, i) do { *(bf16x8*)(V_lds + (b) * SHM_V + vst0) = sr_[i].vs0;          \
;     *(bf16x8*)(V_lds + (b) * SHM_V + vst1) = sr_[i].vs1; int kc = sc * 2;               \
;     *(bf16x8*)(K_lds + (b) * SHM_K + KSWZ(sr, kc)) = sr_[i].ks0;                       \
;     *(bf16x8*)(K_lds + (b) * SHM_K + KSWZ(32 + sr, kc)) = sr_[i].ks1; } while (0)
; #define SWAIT() asm volatile("s_waitcnt vmcnt(0)" ::: "memory")
; #define RESC(a) do { if (__any((a) < 1.f)) { if (hi == 0) al_l[r32] = (a); asm volatile("s_waitcnt lgkmcnt(0)" ::: "memory"); \
;     _Pragma("unroll") for (int d = 0; d < 4; ++d) _Pragma("unroll") for (int r = 0; r < 16; ++r) o[d][r] *= al_l[crow(r, hi)]; } } while (0)
; __device__ __forceinline__ void partialSM(f32x16& p0, f32x16& p1, float& m_reg, float& mn, float& alpha) {
;     ...
;     if (__builtin_expect(__all(pmax - m_reg <= THR / SCALE), 1)) { mn = m_reg; alpha = 1.f; }
;     else { mn = fmaxf(m_reg, pmax); alpha = __builtin_amdgcn_exp2f((m_reg - mn) * C); m_reg = mn; }
;     const float mnC = -mn * C;
; #pragma unroll
;     for (int r = 0; r < 16; ++r) p0[r] = fmaf(p0[r], C, mnC);
; #pragma unroll
;     for (int r = 0; r < 16; ++r) p1[r] = fmaf(p1[r], C, mnC);
; #pragma unroll
;     for (int r = 0; r < 16; ++r) p0[r] = __builtin_amdgcn_exp2f(p0[r]);
; __device__ __forceinline__ void attn_unit(const bf16_t* Qb, const bf16_t* Kh, const bf16_t* Vh, bf16_t* Ob, float* scr, int seq, float lam, float onemli, const float* subg, char* lds) {
;     ...
;         f32x16 pA0, pA1, pB0, pB1; float mnA, mnB, alA, alB; bf16x8 pa0, pa1, pa2, pa3;
;         constexpr int SE = 0, SO = 0;
;         __syncthreads();
;         SLOAD(SE, 0); asm volatile("s_waitcnt vmcnt(0)" ::: "memory"); SWRITE(0, SE); __syncthreads();
;         qkt(pA0, pA1, K_lds, qr, r32, hi, comp); partialSM(pA0, pA1, m_reg, mnA, alA);
;         SLOAD(SO, KVBLK);
;         SWAIT(); SWRITE(1, SO); __syncthreads();
;         for (int j = 1; j + 1 < NT; j += 2) {
;             SBAR(); qkt(pB0, pB1, K_lds + SHM_K, qr, r32, hi, comp);
;             finishSM(pA0, pA1, alA, l_reg, pa0, pa1, pa2, pa3); SBAR();
;             SLOAD(SO, (j + 1) * KVBLK); SBAR();
;             pv_d0(o, vb0, pa0, pa1, pa2, pa3); partialSM(pB0, pB1, m_reg, mnB, alB);
;             __syncthreads(); SWAIT(); SWRITE(0, SE);
;             RESC(alB); __syncthreads();
	v_mfma_f32_32x32x16_bf16 v[32:47], v[212:215], v[220:223], v[32:47]
	ds_read_b64_tr_b16 v[220:221], v160 offset:0x400
	ds_read_b64_tr_b16 v[222:223], v160 offset:0xc00
	v_max_f32_e32 v255, v255, v255
	v_max_f32_e32 v179, v179, v179
	v_max_f32_e32 v179, v179, v255
	v_sub_f32_e32 v255, v179, v175
	v_cmp_ge_f32_e32 vcc, s65, v255
	v_mfma_f32_32x32x16_bf16 v[32:47], v[180:183], v[224:227], v[32:47]
	ds_read_b64_tr_b16 v[224:225], v160 offset:0x1400
	ds_read_b64_tr_b16 v[226:227], v160 offset:0x1c00
	v_max_f32_e32 v255, v175, v175
	v_max_f32_e32 v179, v255, v179
	v_sub_f32_e32 v255, v175, v179
	v_mul_f32_e32 v255, 0x3e38aa3b, v255
	v_exp_f32_e32 v255, v255
	v_mfma_f32_32x32x16_bf16 v[32:47], v[184:187], v[228:231], v[32:47]
	ds_read_b64_tr_b16 v[228:229], v160 offset:0x2400
	ds_read_b64_tr_b16 v[230:231], v160 offset:0x2c00
	s_cmp_eq_u64 vcc, exec
	s_cselect_b64 s[8:9], -1, 0
	v_cndmask_b32_e64 v255, v255, 1.0, s[8:9]
	v_cndmask_b32_e64 v175, v179, v175, s[8:9]
	v_mul_f32_e32 v179, 0xbe38aa3b, v175
	v_mfma_f32_32x32x16_bf16 v[32:47], v[216:219], v[232:235], v[32:47]
	ds_read_b64_tr_b16 v[232:233], v160 offset:0x3400
	ds_read_b64_tr_b16 v[234:235], v160 offset:0x3c00
	v_pk_fma_f32 v[80:81], v[80:81], s[72:73], v[178:179] op_sel:[0,0,1] op_sel_hi:[1,0,1]
	v_pk_fma_f32 v[82:83], v[82:83], s[72:73], v[178:179] op_sel:[0,0,1] op_sel_hi:[1,0,1]
	v_pk_fma_f32 v[84:85], v[84:85], s[72:73], v[178:179] op_sel:[0,0,1] op_sel_hi:[1,0,1]
	v_pk_fma_f32 v[86:87], v[86:87], s[72:73], v[178:179] op_sel:[0,0,1] op_sel_hi:[1,0,1]
	v_pk_fma_f32 v[88:89], v[88:89], s[72:73], v[178:179] op_sel:[0,0,1] op_sel_hi:[1,0,1]
	s_waitcnt lgkmcnt(0)
	v_mfma_f32_32x32x16_bf16 v[16:31], v[212:215], v[220:223], v[16:31]
	ds_read_b64_tr_b16 v[220:221], v160 offset:0x600
	ds_read_b64_tr_b16 v[222:223], v160 offset:0xe00
	v_pk_fma_f32 v[90:91], v[90:91], s[72:73], v[178:179] op_sel:[0,0,1] op_sel_hi:[1,0,1]
	v_pk_fma_f32 v[92:93], v[92:93], s[72:73], v[178:179] op_sel:[0,0,1] op_sel_hi:[1,0,1]
	v_pk_fma_f32 v[94:95], v[94:95], s[72:73], v[178:179] op_sel:[0,0,1] op_sel_hi:[1,0,1]
	v_exp_f32_e32 v127, v80
	v_mfma_f32_32x32x16_bf16 v[16:31], v[180:183], v[224:227], v[16:31]
	ds_read_b64_tr_b16 v[224:225], v160 offset:0x1600
	ds_read_b64_tr_b16 v[226:227], v160 offset:0x1e00
	v_exp_f32_e32 v129, v81
	v_exp_f32_e32 v125, v82
	v_exp_f32_e32 v128, v83
	v_mfma_f32_32x32x16_bf16 v[16:31], v[184:187], v[228:231], v[16:31]
	ds_read_b64_tr_b16 v[228:229], v160 offset:0x2600
	ds_read_b64_tr_b16 v[230:231], v160 offset:0x2e00
	v_exp_f32_e32 v123, v84
	v_exp_f32_e32 v126, v85
	v_exp_f32_e32 v122, v86
	v_mfma_f32_32x32x16_bf16 v[16:31], v[216:219], v[232:235], v[16:31]
	ds_read_b64_tr_b16 v[232:233], v160 offset:0x3600
	ds_read_b64_tr_b16 v[234:235], v160 offset:0x3e00
	v_exp_f32_e32 v124, v87
	v_exp_f32_e32 v119, v88
	v_exp_f32_e32 v121, v89
	s_waitcnt lgkmcnt(0)
	v_mfma_f32_32x32x16_bf16 v[0:15], v[212:215], v[220:223], v[0:15]
	s_barrier
	s_waitcnt vmcnt(0)
	s_waitcnt vmcnt(3)
	ds_write_b128 v163, v[240:243]
	s_waitcnt vmcnt(1)
	ds_write_b128 v164, v[206:209]
	ds_write_b128 v161, v[244:247] offset:32768
	s_waitcnt vmcnt(0)
	ds_write_b128 v162, v[248:251] offset:32768
	v_exp_f32_e32 v117, v90
	v_exp_f32_e32 v120, v91
	v_exp_f32_e32 v115, v92
	v_mfma_f32_32x32x16_bf16 v[0:15], v[180:183], v[224:227], v[0:15]
	v_exp_f32_e32 v118, v93
	v_exp_f32_e32 v114, v94
	v_exp_f32_e32 v116, v95
	v_mfma_f32_32x32x16_bf16 v[0:15], v[184:187], v[228:231], v[0:15]
	v_mfma_f32_32x32x16_bf16 v[0:15], v[216:219], v[232:235], v[0:15]
	v_mov_b32_e32 v180, v255
	v_cmp_gt_f32_e32 vcc, 1.0, v180
	s_cbranch_vccz .LBB0_266
	s_and_saveexec_b64 s[2:3], s[6:7]
	ds_write_b32 v157, v180 offset:128
	s_or_b64 exec, exec, s[2:3]
	s_waitcnt lgkmcnt(0)
	ds_read_b128 v[240:243], v158 offset:224
	ds_read_b128 v[244:247], v158 offset:192
	ds_read_b128 v[248:251], v158 offset:160
	ds_read_b128 v[206:209], v158 offset:128
	s_waitcnt lgkmcnt(3)
	v_pk_mul_f32 v[62:63], v[62:63], v[242:243]
	s_waitcnt lgkmcnt(2)
	v_pk_mul_f32 v[58:59], v[58:59], v[246:247]
	s_waitcnt lgkmcnt(1)
	v_pk_mul_f32 v[54:55], v[54:55], v[250:251]
	s_waitcnt lgkmcnt(0)
	v_pk_mul_f32 v[50:51], v[50:51], v[208:209]
	v_pk_mul_f32 v[60:61], v[60:61], v[240:241]
	v_pk_mul_f32 v[56:57], v[56:57], v[244:245]
	v_pk_mul_f32 v[52:53], v[52:53], v[248:249]
	v_pk_mul_f32 v[48:49], v[48:49], v[206:207]
	v_pk_mul_f32 v[46:47], v[46:47], v[242:243]
	v_pk_mul_f32 v[42:43], v[42:43], v[246:247]
	v_pk_mul_f32 v[38:39], v[38:39], v[250:251]
	v_pk_mul_f32 v[34:35], v[34:35], v[208:209]
	v_pk_mul_f32 v[44:45], v[44:45], v[240:241]
	v_pk_mul_f32 v[40:41], v[40:41], v[244:245]
	v_pk_mul_f32 v[36:37], v[36:37], v[248:249]
	v_pk_mul_f32 v[32:33], v[32:33], v[206:207]
	v_pk_mul_f32 v[30:31], v[30:31], v[242:243]
	v_pk_mul_f32 v[26:27], v[26:27], v[246:247]
	v_pk_mul_f32 v[22:23], v[22:23], v[250:251]
	v_pk_mul_f32 v[18:19], v[18:19], v[208:209]
	v_pk_mul_f32 v[28:29], v[28:29], v[240:241]
	v_pk_mul_f32 v[24:25], v[24:25], v[244:245]
	v_pk_mul_f32 v[20:21], v[20:21], v[248:249]
	v_pk_mul_f32 v[16:17], v[16:17], v[206:207]
	v_pk_mul_f32 v[14:15], v[14:15], v[242:243]
	v_pk_mul_f32 v[10:11], v[10:11], v[246:247]
	v_pk_mul_f32 v[6:7], v[6:7], v[250:251]
	v_pk_mul_f32 v[2:3], v[2:3], v[208:209]
	v_pk_mul_f32 v[12:13], v[12:13], v[240:241]
	v_pk_mul_f32 v[8:9], v[8:9], v[244:245]
	v_pk_mul_f32 v[4:5], v[4:5], v[248:249]
	v_pk_mul_f32 v[0:1], v[0:1], v[206:207]
; __device__ __forceinline__ void partialSM(f32x16& p0, f32x16& p1, float& m_reg, float& mn, float& alpha) {
;     constexpr float C = SCALE * 1.4426950408889634f;
;     float pmax = p0[0];
; #pragma unroll
;     for (int r = 1; r < 16; ++r) pmax = fmaxf(pmax, p0[r]);
; #pragma unroll
;     for (int r = 0; r < 16; ++r) pmax = fmaxf(pmax, p1[r]);
;     { auto rr = __builtin_amdgcn_permlane32_swap(__float_as_uint(pmax), __float_as_uint(pmax), false, false);
;       pmax = fmaxf(__uint_as_float(rr[0]), __uint_as_float(rr[1])); }
;     if (__builtin_expect(__all(pmax - m_reg <= THR / SCALE), 1)) { mn = m_reg; alpha = 1.f; }
;     else { mn = fmaxf(m_reg, pmax); alpha = __builtin_amdgcn_exp2f((m_reg - mn) * C); m_reg = mn; }
;     const float mnC = -mn * C;
; #pragma unroll
;     for (int r = 0; r < 16; ++r) p0[r] = fmaf(p0[r], C, mnC);
; #pragma unroll
;     for (int r = 0; r < 16; ++r) p1[r] = fmaf(p1[r], C, mnC);
; #pragma unroll
;     for (int r = 0; r < 16; ++r) p0[r] = __builtin_amdgcn_exp2f(p0[r]);
; }
; __device__ __forceinline__ void finishSM(f32x16& p0, f32x16& p1, float alpha, float& l_reg, bf16x8& pa0, bf16x8& pa1, bf16x8& pa2, bf16x8& pa3) {
; #pragma unroll
;     for (int r = 0; r < 16; ++r) p1[r] = __builtin_amdgcn_exp2f(p1[r]);
;     float ps = 0;
; #pragma unroll
;     for (int r = 0; r < 16; ++r) ps += p0[r];
; #pragma unroll
;     for (int r = 0; r < 16; ++r) ps += p1[r];
;     { auto rr = __builtin_amdgcn_permlane32_swap(__float_as_uint(ps), __float_as_uint(ps), false, false);
;       ps = __uint_as_float(rr[0]) + __uint_as_float(rr[1]); }
;     l_reg = l_reg * alpha + ps;
;     ...
;     PK4(p0, 0, pa0); PK4(p0, 8, pa1); PK4(p1, 0, pa2); PK4(p1, 8, pa3);
;     ...
; }
; __device__ __forceinline__ void qkt(f32x16& p0, f32x16& p1, const char* Ks, const bf16x8* qr, int r32, int hi, int comp) {
;     p0 = f32x16{}; p1 = f32x16{};
; #pragma unroll
;     for (int d0 = 0; d0 < 4; ++d0) { const int cb = (comp * 64 + d0 * 16 + hi * 8) * 2;
;         const bf16x8 b0 = *reinterpret_cast<const bf16x8*>(Ks + KSWZ(r32, cb));
;         const bf16x8 b1 = *reinterpret_cast<const bf16x8*>(Ks + KSWZ(32 + r32, cb));
;         p0 = __builtin_amdgcn_mfma_f32_32x32x16_bf16(b0, qr[d0], p0, 0, 0, 0);
;         p1 = __builtin_amdgcn_mfma_f32_32x32x16_bf16(b1, qr[d0], p1, 0, 0, 0); }
; }
.LBB0_266:
	v_fmamk_f32 v189, v64, 0x3e38aa3b, v179
	v_fmamk_f32 v211, v65, 0x3e38aa3b, v179
	v_fmamk_f32 v212, v66, 0x3e38aa3b, v179
	v_fmamk_f32 v213, v67, 0x3e38aa3b, v179
	v_fmamk_f32 v214, v68, 0x3e38aa3b, v179
	v_fmamk_f32 v182, v69, 0x3e38aa3b, v179
	v_fmamk_f32 v183, v70, 0x3e38aa3b, v179
	v_fmamk_f32 v184, v71, 0x3e38aa3b, v179
	v_fmamk_f32 v185, v72, 0x3e38aa3b, v179
	v_fmamk_f32 v186, v73, 0x3e38aa3b, v179
	v_fmamk_f32 v187, v74, 0x3e38aa3b, v179
	v_fmamk_f32 v188, v75, 0x3e38aa3b, v179
	v_fmamk_f32 v181, v76, 0x3e38aa3b, v179
	v_fmamk_f32 v215, v77, 0x3e38aa3b, v179
	v_fmamk_f32 v216, v78, 0x3e38aa3b, v179
	v_fmac_f32_e32 v179, 0x3e38aa3b, v79
	s_waitcnt lgkmcnt(0)
	s_barrier
	ds_read_b128 v[64:67], v170 offset:32768
	ds_read_b128 v[68:71], v170 offset:40960
	v_exp_f32_e32 v203, v181
	v_add_f32_e32 v181, 0, v127
	v_add_f32_e32 v181, v129, v181
	s_waitcnt lgkmcnt(1)
	v_mfma_f32_32x32x16_bf16 v[80:95], v[64:67], v[110:113], 0
	v_add_f32_e32 v181, v125, v181
	v_add_f32_e32 v181, v128, v181
	v_add_f32_e32 v181, v123, v181
	ds_read_b128 v[218:221], v171 offset:32768
	ds_read_b128 v[222:225], v171 offset:40960
	v_add_f32_e32 v181, v126, v181
	v_add_f32_e32 v181, v122, v181
	v_add_f32_e32 v181, v124, v181
	s_waitcnt lgkmcnt(2)
	v_mfma_f32_32x32x16_bf16 v[64:79], v[68:71], v[110:113], 0
	v_add_f32_e32 v181, v119, v181
	v_add_f32_e32 v181, v121, v181
	v_add_f32_e32 v181, v117, v181
	v_add_f32_e32 v181, v120, v181
	v_exp_f32_e32 v189, v189
	v_add_f32_e32 v181, v115, v181
	v_exp_f32_e32 v190, v211
	s_waitcnt lgkmcnt(1)
	v_mfma_f32_32x32x16_bf16 v[80:95], v[218:221], v[106:109], v[80:95]
	v_add_f32_e32 v181, v118, v181
	v_exp_f32_e32 v191, v212
	v_add_f32_e32 v181, v114, v181
	v_exp_f32_e32 v192, v213
	v_add_f32_e32 v181, v116, v181
	v_exp_f32_e32 v193, v214
	v_add_f32_e32 v181, v189, v181
	s_waitcnt lgkmcnt(0)
	v_mfma_f32_32x32x16_bf16 v[64:79], v[222:225], v[106:109], v[64:79]
	ds_read_b128 v[218:221], v173 offset:32768
	ds_read_b128 v[222:225], v173 offset:40960
	v_exp_f32_e32 v194, v182
	v_add_f32_e32 v181, v190, v181
	v_exp_f32_e32 v183, v183
	v_add_f32_e32 v181, v191, v181
	v_exp_f32_e32 v195, v184
	v_add_f32_e32 v181, v192, v181
	s_waitcnt lgkmcnt(1)
	v_mfma_f32_32x32x16_bf16 v[80:95], v[218:221], v[102:105], v[80:95]
	v_exp_f32_e32 v200, v185
	v_add_f32_e32 v181, v193, v181
	v_exp_f32_e32 v201, v186
	v_add_f32_e32 v181, v194, v181
	v_exp_f32_e32 v202, v187
	v_add_f32_e32 v181, v183, v181
	v_exp_f32_e32 v188, v188
	s_waitcnt lgkmcnt(0)
	v_mfma_f32_32x32x16_bf16 v[64:79], v[222:225], v[102:105], v[64:79]
	ds_read_b128 v[218:221], v172 offset:32768
	ds_read_b128 v[222:225], v172 offset:40960
	v_add_f32_e32 v181, v195, v181
	v_add_f32_e32 v181, v200, v181
	v_exp_f32_e32 v204, v215
	v_add_f32_e32 v181, v201, v181
	v_exp_f32_e32 v205, v216
	v_add_f32_e32 v181, v202, v181
	s_waitcnt lgkmcnt(1)
	v_mfma_f32_32x32x16_bf16 v[80:95], v[218:221], v[98:101], v[80:95]
	v_exp_f32_e32 v179, v179
	v_add_f32_e32 v181, v188, v181
	v_add_f32_e32 v181, v203, v181
	v_add_f32_e32 v181, v204, v181
	v_add_f32_e32 v181, v205, v181
	v_add_f32_e32 v181, v179, v181
	v_mov_b32_e32 v182, v181
	s_waitcnt lgkmcnt(0)
	v_mfma_f32_32x32x16_bf16 v[64:79], v[222:225], v[98:101], v[64:79]
	v_permlane32_swap_b32_e32 v181, v182
	v_cvt_pk_bf16_f32 v184, v127, v129
	v_cvt_pk_bf16_f32 v185, v125, v128
	v_cvt_pk_bf16_f32 v186, v123, v126
	v_cvt_pk_bf16_f32 v187, v122, v124
	v_cvt_pk_bf16_f32 v212, v119, v121
	v_cvt_pk_bf16_f32 v213, v117, v120
	v_cvt_pk_bf16_f32 v214, v115, v118
	v_cvt_pk_bf16_f32 v215, v114, v116
	v_cvt_pk_bf16_f32 v216, v189, v190
	v_cvt_pk_bf16_f32 v217, v191, v192
	v_cvt_pk_bf16_f32 v218, v193, v194
	v_cvt_pk_bf16_f32 v219, v183, v195
	v_cvt_pk_bf16_f32 v220, v200, v201
	v_cvt_pk_bf16_f32 v221, v202, v188
	v_cvt_pk_bf16_f32 v222, v203, v204
	v_cvt_pk_bf16_f32 v223, v205, v179
	s_nop 0
	v_permlane32_swap_b32_e32 v184, v186
	v_permlane32_swap_b32_e32 v185, v187
	v_permlane32_swap_b32_e32 v212, v214
	v_permlane32_swap_b32_e32 v213, v215
	v_permlane32_swap_b32_e32 v216, v218
	v_permlane32_swap_b32_e32 v217, v219
	v_permlane32_swap_b32_e32 v220, v222
	v_permlane32_swap_b32_e32 v221, v223
	v_add_u32_e32 v118, 0x20000, v176
	v_add_u32_e32 v122, 0x30000, v176
	global_load_dwordx4 v[114:117], v118, s[58:59]
	s_nop 0
	global_load_dwordx4 v[118:121], v118, s[28:29]
	s_nop 0
	global_load_dwordx4 v[126:129], v122, s[58:59]
	s_nop 0
	global_load_dwordx4 v[122:125], v122, s[28:29]
	ds_read_b64_tr_b16 v[224:225], v159 offset:0
	ds_read_b64_tr_b16 v[226:227], v159 offset:0x800
	ds_read_b64_tr_b16 v[228:229], v159 offset:0x1000
	ds_read_b64_tr_b16 v[230:231], v159 offset:0x1800
	ds_read_b64_tr_b16 v[232:233], v159 offset:0x2000
	ds_read_b64_tr_b16 v[234:235], v159 offset:0x2800
	ds_read_b64_tr_b16 v[236:237], v159 offset:0x3000
	ds_read_b64_tr_b16 v[238:239], v159 offset:0x3800
	s_waitcnt lgkmcnt(0)
	s_nop 0
	v_mfma_f32_32x32x16_bf16 v[48:63], v[184:187], v[224:227], v[48:63]
	ds_read_b64_tr_b16 v[224:225], v159 offset:0x200
	ds_read_b64_tr_b16 v[226:227], v159 offset:0xa00
	v_max_f32_e32 v255, v81, v81
	v_max_f32_e32 v210, v80, v80
	v_max3_f32 v183, v64, v65, v66
	v_max_f32_e32 v255, v210, v255
	v_max3_f32 v183, v183, v67, v68
	v_mfma_f32_32x32x16_bf16 v[48:63], v[212:215], v[228:231], v[48:63]
	ds_read_b64_tr_b16 v[228:229], v159 offset:0x1200
	ds_read_b64_tr_b16 v[230:231], v159 offset:0x1a00
	v_max3_f32 v255, v255, v82, v83
	v_max3_f32 v183, v183, v69, v70
	v_max3_f32 v255, v255, v84, v85
	v_max3_f32 v183, v183, v71, v72
	v_max3_f32 v255, v255, v86, v87
	v_mfma_f32_32x32x16_bf16 v[48:63], v[216:219], v[232:235], v[48:63]
	ds_read_b64_tr_b16 v[232:233], v159 offset:0x2200
	ds_read_b64_tr_b16 v[234:235], v159 offset:0x2a00
	v_max3_f32 v183, v183, v73, v74
	v_max3_f32 v255, v255, v88, v89
	v_max3_f32 v183, v183, v75, v76
	v_max3_f32 v255, v255, v90, v91
	v_max3_f32 v183, v183, v77, v78
	v_mfma_f32_32x32x16_bf16 v[48:63], v[220:223], v[236:239], v[48:63]
	ds_read_b64_tr_b16 v[236:237], v159 offset:0x3200
	ds_read_b64_tr_b16 v[238:239], v159 offset:0x3a00
	v_max3_f32 v255, v255, v92, v93
	v_max_f32_e32 v183, v79, v183
	v_max3_f32 v255, v255, v94, v95
	v_max_f32_e32 v255, v255, v183
	v_mov_b32_e32 v210, v255
	s_nop 1
	v_permlane32_swap_b32_e32 v255, v210
	s_waitcnt lgkmcnt(0)
; __device__ __forceinline__ void partialSM(f32x16& p0, f32x16& p1, float& m_reg, float& mn, float& alpha) {
;     ...
;     { auto rr = __builtin_amdgcn_permlane32_swap(__float_as_uint(pmax), __float_as_uint(pmax), false, false);
;       pmax = fmaxf(__uint_as_float(rr[0]), __uint_as_float(rr[1])); }
;     if (__builtin_expect(__all(pmax - m_reg <= THR / SCALE), 1)) { mn = m_reg; alpha = 1.f; }
;     else { mn = fmaxf(m_reg, pmax); alpha = __builtin_amdgcn_exp2f((m_reg - mn) * C); m_reg = mn; }
;     const float mnC = -mn * C;
; #pragma unroll
;     for (int r = 0; r < 16; ++r) p0[r] = fmaf(p0[r], C, mnC);
; #pragma unroll
;     for (int r = 0; r < 16; ++r) p1[r] = fmaf(p1[r], C, mnC);
; #pragma unroll
;     for (int r = 0; r < 16; ++r) p0[r] = __builtin_amdgcn_exp2f(p0[r]);
; }
	v_mfma_f32_32x32x16_bf16 v[32:47], v[184:187], v[224:227], v[32:47]
	ds_read_b64_tr_b16 v[224:225], v159 offset:0x400
	ds_read_b64_tr_b16 v[226:227], v159 offset:0xc00
	v_max_f32_e32 v210, v210, v210
	v_max_f32_e32 v255, v255, v255
	v_max_f32_e32 v255, v255, v210
	v_sub_f32_e32 v210, v255, v175
	v_cmp_ge_f32_e32 vcc, s65, v210
	v_mfma_f32_32x32x16_bf16 v[32:47], v[212:215], v[228:231], v[32:47]
	ds_read_b64_tr_b16 v[228:229], v159 offset:0x1400
	ds_read_b64_tr_b16 v[230:231], v159 offset:0x1c00
	v_max_f32_e32 v210, v175, v175
	v_max_f32_e32 v210, v210, v255
	v_sub_f32_e32 v255, v175, v210
	v_mul_f32_e32 v255, 0x3e38aa3b, v255
	v_exp_f32_e32 v255, v255
	v_mfma_f32_32x32x16_bf16 v[32:47], v[216:219], v[232:235], v[32:47]
	ds_read_b64_tr_b16 v[232:233], v159 offset:0x2400
	ds_read_b64_tr_b16 v[234:235], v159 offset:0x2c00
	s_cmp_eq_u64 vcc, exec
	s_cselect_b64 s[8:9], -1, 0
	v_cndmask_b32_e64 v255, v255, 1.0, s[8:9]
	v_cndmask_b32_e64 v175, v210, v175, s[8:9]
	v_mul_f32_e32 v210, 0xbe38aa3b, v175
	v_mfma_f32_32x32x16_bf16 v[32:47], v[220:223], v[236:239], v[32:47]
	ds_read_b64_tr_b16 v[236:237], v159 offset:0x3400
	ds_read_b64_tr_b16 v[238:239], v159 offset:0x3c00
	v_pk_fma_f32 v[80:81], v[80:81], s[72:73], v[210:211] op_sel_hi:[1,0,0]
	v_pk_fma_f32 v[82:83], v[82:83], s[72:73], v[210:211] op_sel_hi:[1,0,0]
	v_pk_fma_f32 v[84:85], v[84:85], s[72:73], v[210:211] op_sel_hi:[1,0,0]
	v_pk_fma_f32 v[86:87], v[86:87], s[72:73], v[210:211] op_sel_hi:[1,0,0]
	v_pk_fma_f32 v[88:89], v[88:89], s[72:73], v[210:211] op_sel_hi:[1,0,0]
	s_waitcnt lgkmcnt(0)
	v_mfma_f32_32x32x16_bf16 v[16:31], v[184:187], v[224:227], v[16:31]
	ds_read_b64_tr_b16 v[224:225], v159 offset:0x600
	ds_read_b64_tr_b16 v[226:227], v159 offset:0xe00
	v_pk_fma_f32 v[90:91], v[90:91], s[72:73], v[210:211] op_sel_hi:[1,0,0]
	v_pk_fma_f32 v[92:93], v[92:93], s[72:73], v[210:211] op_sel_hi:[1,0,0]
	v_pk_fma_f32 v[94:95], v[94:95], s[72:73], v[210:211] op_sel_hi:[1,0,0]
	v_exp_f32_e32 v240, v80
	v_mfma_f32_32x32x16_bf16 v[16:31], v[212:215], v[228:231], v[16:31]
	ds_read_b64_tr_b16 v[228:229], v159 offset:0x1600
	ds_read_b64_tr_b16 v[230:231], v159 offset:0x1e00
	v_exp_f32_e32 v241, v81
	v_exp_f32_e32 v242, v82
	v_exp_f32_e32 v243, v83
	v_mfma_f32_32x32x16_bf16 v[16:31], v[216:219], v[232:235], v[16:31]
	ds_read_b64_tr_b16 v[232:233], v159 offset:0x2600
	ds_read_b64_tr_b16 v[234:235], v159 offset:0x2e00
	v_exp_f32_e32 v244, v84
	v_exp_f32_e32 v245, v85
	v_exp_f32_e32 v246, v86
	v_mfma_f32_32x32x16_bf16 v[16:31], v[220:223], v[236:239], v[16:31]
	ds_read_b64_tr_b16 v[236:237], v159 offset:0x3600
	ds_read_b64_tr_b16 v[238:239], v159 offset:0x3e00
	v_exp_f32_e32 v247, v87
	v_exp_f32_e32 v248, v88
	v_exp_f32_e32 v249, v89
	s_waitcnt lgkmcnt(0)
	v_mfma_f32_32x32x16_bf16 v[0:15], v[184:187], v[224:227], v[0:15]
	s_barrier
	s_waitcnt vmcnt(0)
	s_waitcnt vmcnt(3)
	ds_write_b128 v163, v[114:117] offset:16384
	s_waitcnt vmcnt(1)
	ds_write_b128 v164, v[126:129] offset:16384
	ds_write_b128 v161, v[118:121] offset:49152
	s_waitcnt vmcnt(0)
	ds_write_b128 v162, v[122:125] offset:49152
	v_exp_f32_e32 v250, v90
	v_exp_f32_e32 v251, v91
	v_exp_f32_e32 v206, v92
	v_mfma_f32_32x32x16_bf16 v[0:15], v[212:215], v[228:231], v[0:15]
	v_exp_f32_e32 v207, v93
	v_exp_f32_e32 v208, v94
	v_exp_f32_e32 v209, v95
	v_mfma_f32_32x32x16_bf16 v[0:15], v[216:219], v[232:235], v[0:15]
	v_mfma_f32_32x32x16_bf16 v[0:15], v[220:223], v[236:239], v[0:15]
	v_mov_b32_e32 v179, v255
	v_cmp_gt_f32_e32 vcc, 1.0, v179
	s_cbranch_vccz .LBB0_270
	s_and_saveexec_b64 s[2:3], s[6:7]
	ds_write_b32 v157, v179 offset:128
	s_or_b64 exec, exec, s[2:3]
	s_waitcnt lgkmcnt(0)
	ds_read_b128 v[114:117], v158 offset:224
	ds_read_b128 v[118:121], v158 offset:192
	ds_read_b128 v[122:125], v158 offset:160
	ds_read_b128 v[126:129], v158 offset:128
	s_waitcnt lgkmcnt(3)
	v_pk_mul_f32 v[62:63], v[62:63], v[116:117]
	s_waitcnt lgkmcnt(2)
	v_pk_mul_f32 v[58:59], v[58:59], v[120:121]
	s_waitcnt lgkmcnt(1)
	v_pk_mul_f32 v[54:55], v[54:55], v[124:125]
	s_waitcnt lgkmcnt(0)
	v_pk_mul_f32 v[50:51], v[50:51], v[128:129]
	v_pk_mul_f32 v[60:61], v[60:61], v[114:115]
	v_pk_mul_f32 v[56:57], v[56:57], v[118:119]
	v_pk_mul_f32 v[52:53], v[52:53], v[122:123]
	v_pk_mul_f32 v[48:49], v[48:49], v[126:127]
	v_pk_mul_f32 v[46:47], v[46:47], v[116:117]
	v_pk_mul_f32 v[42:43], v[42:43], v[120:121]
	v_pk_mul_f32 v[38:39], v[38:39], v[124:125]
	v_pk_mul_f32 v[34:35], v[34:35], v[128:129]
	v_pk_mul_f32 v[44:45], v[44:45], v[114:115]
	v_pk_mul_f32 v[40:41], v[40:41], v[118:119]
	v_pk_mul_f32 v[36:37], v[36:37], v[122:123]
	v_pk_mul_f32 v[32:33], v[32:33], v[126:127]
	v_pk_mul_f32 v[30:31], v[30:31], v[116:117]
	v_pk_mul_f32 v[26:27], v[26:27], v[120:121]
	v_pk_mul_f32 v[22:23], v[22:23], v[124:125]
	v_pk_mul_f32 v[18:19], v[18:19], v[128:129]
	v_pk_mul_f32 v[28:29], v[28:29], v[114:115]
	v_pk_mul_f32 v[24:25], v[24:25], v[118:119]
	v_pk_mul_f32 v[20:21], v[20:21], v[122:123]
	v_pk_mul_f32 v[16:17], v[16:17], v[126:127]
	v_pk_mul_f32 v[14:15], v[14:15], v[116:117]
	v_pk_mul_f32 v[10:11], v[10:11], v[120:121]
	v_pk_mul_f32 v[6:7], v[6:7], v[124:125]
	v_pk_mul_f32 v[2:3], v[2:3], v[128:129]
	v_pk_mul_f32 v[12:13], v[12:13], v[114:115]
	v_pk_mul_f32 v[8:9], v[8:9], v[118:119]
	v_pk_mul_f32 v[4:5], v[4:5], v[122:123]
	v_pk_mul_f32 v[0:1], v[0:1], v[126:127]

; __device__ __forceinline__ void partialSM(f32x16& p0, f32x16& p1, float& m_reg, float& mn, float& alpha) {
;     constexpr float C = SCALE * 1.4426950408889634f;
;     float pmax = p0[0];
; #pragma unroll
;     for (int r = 1; r < 16; ++r) pmax = fmaxf(pmax, p0[r]);
; #pragma unroll
;     for (int r = 0; r < 16; ++r) pmax = fmaxf(pmax, p1[r]);
;     { auto rr = __builtin_amdgcn_permlane32_swap(__float_as_uint(pmax), __float_as_uint(pmax), false, false);
;       pmax = fmaxf(__uint_as_float(rr[0]), __uint_as_float(rr[1])); }
;     if (__builtin_expect(__all(pmax - m_reg <= THR / SCALE), 1)) { mn = m_reg; alpha = 1.f; }
;     else { mn = fmaxf(m_reg, pmax); alpha = __builtin_amdgcn_exp2f((m_reg - mn) * C); m_reg = mn; }
;     const float mnC = -mn * C;
; #pragma unroll
;     for (int r = 0; r < 16; ++r) p0[r] = fmaf(p0[r], C, mnC);
; #pragma unroll
;     for (int r = 0; r < 16; ++r) p1[r] = fmaf(p1[r], C, mnC);
; #pragma unroll
;     for (int r = 0; r < 16; ++r) p0[r] = __builtin_amdgcn_exp2f(p0[r]);
; }
; __device__ __forceinline__ void finishSM(f32x16& p0, f32x16& p1, float alpha, float& l_reg, bf16x8& pa0, bf16x8& pa1, bf16x8& pa2, bf16x8& pa3) {
; #pragma unroll
;     for (int r = 0; r < 16; ++r) p1[r] = __builtin_amdgcn_exp2f(p1[r]);
;     float ps = 0;
; #pragma unroll
;     for (int r = 0; r < 16; ++r) ps += p0[r];
; #pragma unroll
;     for (int r = 0; r < 16; ++r) ps += p1[r];
;     { auto rr = __builtin_amdgcn_permlane32_swap(__float_as_uint(ps), __float_as_uint(ps), false, false);
;       ps = __uint_as_float(rr[0]) + __uint_as_float(rr[1]); }
;     l_reg = l_reg * alpha + ps;
;     ...
;     PK4(p0, 0, pa0); PK4(p0, 8, pa1); PK4(p1, 0, pa2); PK4(p1, 8, pa3);
;     ...
; }
; __device__ __forceinline__ void qkt(f32x16& p0, f32x16& p1, const char* Ks, const bf16x8* qr, int r32, int hi, int comp) {
;     p0 = f32x16{}; p1 = f32x16{};
; #pragma unroll
;     for (int d0 = 0; d0 < 4; ++d0) { const int cb = (comp * 64 + d0 * 16 + hi * 8) * 2;
;         const bf16x8 b0 = *reinterpret_cast<const bf16x8*>(Ks + KSWZ(r32, cb));
;         const bf16x8 b1 = *reinterpret_cast<const bf16x8*>(Ks + KSWZ(32 + r32, cb));
;         p0 = __builtin_amdgcn_mfma_f32_32x32x16_bf16(b0, qr[d0], p0, 0, 0, 0);
;         p1 = __builtin_amdgcn_mfma_f32_32x32x16_bf16(b1, qr[d0], p1, 0, 0, 0); }
; }
.LBB0_280:
	ds_read_b128 v[64:67], v140 offset:49152
	ds_read_b128 v[68:71], v140 offset:57344
	v_add_f32_e32 v135, 0, v240
	v_add_f32_e32 v135, v241, v135
	v_add_f32_e32 v135, v242, v135
	s_waitcnt lgkmcnt(1)
	v_mfma_f32_32x32x16_bf16 v[80:95], v[64:67], v[110:113], 0
	v_add_f32_e32 v135, v243, v135
	v_add_f32_e32 v135, v244, v135
	ds_read_b128 v[136:139], v143 offset:49152
	ds_read_b128 v[178:181], v143 offset:57344
	v_add_f32_e32 v135, v245, v135
	v_add_f32_e32 v135, v246, v135
	v_add_f32_e32 v135, v247, v135
	v_add_f32_e32 v135, v248, v135
	s_waitcnt lgkmcnt(2)
	v_mfma_f32_32x32x16_bf16 v[64:79], v[68:71], v[110:113], 0
	v_add_f32_e32 v135, v249, v135
	v_add_f32_e32 v135, v250, v135
	v_add_f32_e32 v135, v251, v135
	v_exp_f32_e32 v128, v128
	v_add_f32_e32 v135, v206, v135
	v_exp_f32_e32 v129, v129
	v_add_f32_e32 v135, v207, v135
	s_waitcnt lgkmcnt(1)
	v_mfma_f32_32x32x16_bf16 v[80:95], v[136:139], v[106:109], v[80:95]
	v_exp_f32_e32 v126, v126
	v_add_f32_e32 v135, v208, v135
	v_exp_f32_e32 v127, v127
	v_add_f32_e32 v135, v209, v135
	v_exp_f32_e32 v122, v122
	v_add_f32_e32 v135, v128, v135
	v_exp_f32_e32 v123, v123
	s_waitcnt lgkmcnt(0)
	v_mfma_f32_32x32x16_bf16 v[64:79], v[178:181], v[106:109], v[64:79]
	ds_read_b128 v[136:139], v142 offset:49152
	ds_read_b128 v[178:181], v142 offset:57344
	v_add_f32_e32 v135, v129, v135
	v_exp_f32_e32 v118, v118
	v_add_f32_e32 v135, v126, v135
	v_exp_f32_e32 v119, v119
	v_add_f32_e32 v135, v127, v135
	v_exp_f32_e32 v116, v116
	s_waitcnt lgkmcnt(1)
	v_mfma_f32_32x32x16_bf16 v[80:95], v[136:139], v[102:105], v[80:95]
	v_add_f32_e32 v135, v122, v135
	v_exp_f32_e32 v117, v117
	v_add_f32_e32 v135, v123, v135
	v_exp_f32_e32 v124, v124
	v_add_f32_e32 v135, v118, v135
	v_exp_f32_e32 v125, v125
	v_add_f32_e32 v135, v119, v135
	s_waitcnt lgkmcnt(0)
	v_mfma_f32_32x32x16_bf16 v[64:79], v[178:181], v[102:105], v[64:79]
	ds_read_b128 v[136:139], v141 offset:49152
	ds_read_b128 v[178:181], v141 offset:57344
	v_exp_f32_e32 v120, v120
	v_add_f32_e32 v135, v116, v135
	v_exp_f32_e32 v121, v121
	v_add_f32_e32 v135, v117, v135
	v_exp_f32_e32 v114, v114
	v_add_f32_e32 v135, v124, v135
	s_waitcnt lgkmcnt(1)
	v_mfma_f32_32x32x16_bf16 v[80:95], v[136:139], v[98:101], v[80:95]
	v_exp_f32_e32 v115, v115
	v_add_f32_e32 v135, v125, v135
	v_add_f32_e32 v135, v120, v135
	v_add_f32_e32 v135, v121, v135
	v_add_f32_e32 v135, v114, v135
	v_add_f32_e32 v135, v115, v135
	v_mov_b32_e32 v136, v135
	s_waitcnt lgkmcnt(0)
	v_mfma_f32_32x32x16_bf16 v[64:79], v[178:181], v[98:101], v[64:79]
	v_permlane32_swap_b32_e32 v135, v136
	v_cvt_pk_bf16_f32 v178, v240, v241
	v_cvt_pk_bf16_f32 v179, v242, v243
	v_cvt_pk_bf16_f32 v180, v244, v245
	v_cvt_pk_bf16_f32 v181, v246, v247
	v_cvt_pk_bf16_f32 v144, v248, v249
	v_cvt_pk_bf16_f32 v145, v250, v251
	v_cvt_pk_bf16_f32 v146, v206, v207
	v_cvt_pk_bf16_f32 v147, v208, v209
	v_cvt_pk_bf16_f32 v166, v128, v129
	v_cvt_pk_bf16_f32 v167, v126, v127
	v_cvt_pk_bf16_f32 v168, v122, v123
	v_cvt_pk_bf16_f32 v169, v118, v119
	v_cvt_pk_bf16_f32 v170, v116, v117
	v_cvt_pk_bf16_f32 v171, v124, v125
	v_cvt_pk_bf16_f32 v172, v120, v121
	v_cvt_pk_bf16_f32 v173, v114, v115
	s_nop 0
	v_permlane32_swap_b32_e32 v178, v180
	v_permlane32_swap_b32_e32 v179, v181
	v_permlane32_swap_b32_e32 v144, v146
	v_permlane32_swap_b32_e32 v145, v147
	v_permlane32_swap_b32_e32 v166, v168
	v_permlane32_swap_b32_e32 v167, v169
	v_permlane32_swap_b32_e32 v170, v172
	v_permlane32_swap_b32_e32 v171, v173
	v_add_u32_e32 v122, 0x10000, v96
	global_load_dwordx4 v[240:243], v96, s[58:59]
	global_load_dwordx4 v[244:247], v96, s[28:29]
	global_load_dwordx4 v[206:209], v122, s[58:59]
	s_nop 0
	global_load_dwordx4 v[248:251], v122, s[28:29]
	ds_read_b64_tr_b16 v[174:175], v160 offset:0
	ds_read_b64_tr_b16 v[176:177], v160 offset:0x800
	ds_read_b64_tr_b16 v[182:183], v160 offset:0x1000
	ds_read_b64_tr_b16 v[184:185], v160 offset:0x1800
	ds_read_b64_tr_b16 v[186:187], v160 offset:0x2000
	ds_read_b64_tr_b16 v[188:189], v160 offset:0x2800
	ds_read_b64_tr_b16 v[212:213], v160 offset:0x3000
	ds_read_b64_tr_b16 v[214:215], v160 offset:0x3800
	s_waitcnt lgkmcnt(0)
	s_nop 0
	v_mfma_f32_32x32x16_bf16 v[48:63], v[178:181], v[174:177], v[48:63]
	ds_read_b64_tr_b16 v[174:175], v160 offset:0x200
	ds_read_b64_tr_b16 v[176:177], v160 offset:0xa00
	v_max_f32_e32 v137, v81, v81
	v_max_f32_e32 v138, v80, v80
	v_max3_f32 v210, v64, v65, v66
	v_max_f32_e32 v137, v138, v137
	v_max3_f32 v210, v210, v67, v68
	v_mfma_f32_32x32x16_bf16 v[48:63], v[144:147], v[182:185], v[48:63]
	ds_read_b64_tr_b16 v[182:183], v160 offset:0x1200
	ds_read_b64_tr_b16 v[184:185], v160 offset:0x1a00
	v_max3_f32 v137, v137, v82, v83
	v_max3_f32 v210, v210, v69, v70
	v_max3_f32 v137, v137, v84, v85
	v_max3_f32 v210, v210, v71, v72
	v_max3_f32 v137, v137, v86, v87
	v_mfma_f32_32x32x16_bf16 v[48:63], v[166:169], v[186:189], v[48:63]
	ds_read_b64_tr_b16 v[186:187], v160 offset:0x2200
	ds_read_b64_tr_b16 v[188:189], v160 offset:0x2a00
	v_max3_f32 v210, v210, v73, v74
	v_max3_f32 v137, v137, v88, v89
	v_max3_f32 v210, v210, v75, v76
	v_max3_f32 v137, v137, v90, v91
	v_max3_f32 v210, v210, v77, v78
	v_mfma_f32_32x32x16_bf16 v[48:63], v[170:173], v[212:215], v[48:63]
	ds_read_b64_tr_b16 v[212:213], v160 offset:0x3200
	ds_read_b64_tr_b16 v[214:215], v160 offset:0x3a00
	v_max3_f32 v137, v137, v92, v93
	v_max_f32_e32 v210, v79, v210
	v_max3_f32 v137, v137, v94, v95
	v_max_f32_e32 v137, v137, v210
	v_mov_b32_e32 v138, v137
	s_nop 1
	v_permlane32_swap_b32_e32 v137, v138
	s_waitcnt lgkmcnt(0)
; __device__ __forceinline__ void partialSM(f32x16& p0, f32x16& p1, float& m_reg, float& mn, float& alpha) {
;     ...
;     { auto rr = __builtin_amdgcn_permlane32_swap(__float_as_uint(pmax), __float_as_uint(pmax), false, false);
;       pmax = fmaxf(__uint_as_float(rr[0]), __uint_as_float(rr[1])); }
;     if (__builtin_expect(__all(pmax - m_reg <= THR / SCALE), 1)) { mn = m_reg; alpha = 1.f; }
;     else { mn = fmaxf(m_reg, pmax); alpha = __builtin_amdgcn_exp2f((m_reg - mn) * C); m_reg = mn; }
;     const float mnC = -mn * C;
; #pragma unroll
;     for (int r = 0; r < 16; ++r) p0[r] = fmaf(p0[r], C, mnC);
; #pragma unroll
;     for (int r = 0; r < 16; ++r) p1[r] = fmaf(p1[r], C, mnC);
; #pragma unroll
;     for (int r = 0; r < 16; ++r) p0[r] = __builtin_amdgcn_exp2f(p0[r]);
; }
	v_mfma_f32_32x32x16_bf16 v[32:47], v[178:181], v[174:177], v[32:47]
	ds_read_b64_tr_b16 v[174:175], v160 offset:0x400
	ds_read_b64_tr_b16 v[176:177], v160 offset:0xc00
	v_max_f32_e32 v138, v138, v138
	v_max_f32_e32 v137, v137, v137
	v_max_f32_e32 v137, v137, v138
	v_sub_f32_e32 v138, v137, v134
	v_cmp_ge_f32_e32 vcc, s65, v138
	v_mfma_f32_32x32x16_bf16 v[32:47], v[144:147], v[182:185], v[32:47]
	ds_read_b64_tr_b16 v[182:183], v160 offset:0x1400
	ds_read_b64_tr_b16 v[184:185], v160 offset:0x1c00
	v_max_f32_e32 v138, v134, v134
	v_max_f32_e32 v137, v138, v137
	v_sub_f32_e32 v138, v134, v137
	v_mul_f32_e32 v138, 0x3e38aa3b, v138
	v_exp_f32_e32 v138, v138
	v_mfma_f32_32x32x16_bf16 v[32:47], v[166:169], v[186:189], v[32:47]
	ds_read_b64_tr_b16 v[186:187], v160 offset:0x2400
	ds_read_b64_tr_b16 v[188:189], v160 offset:0x2c00
	s_cmp_eq_u64 vcc, exec
	s_cselect_b64 s[8:9], -1, 0
	v_cndmask_b32_e64 v138, v138, 1.0, s[8:9]
	v_cndmask_b32_e64 v134, v137, v134, s[8:9]
	v_mul_f32_e32 v137, 0xbe38aa3b, v134
	v_mfma_f32_32x32x16_bf16 v[32:47], v[170:173], v[212:215], v[32:47]
	ds_read_b64_tr_b16 v[212:213], v160 offset:0x3400
	ds_read_b64_tr_b16 v[214:215], v160 offset:0x3c00
	v_pk_fma_f32 v[80:81], v[80:81], s[72:73], v[136:137] op_sel:[0,0,1] op_sel_hi:[1,0,1]
	v_pk_fma_f32 v[82:83], v[82:83], s[72:73], v[136:137] op_sel:[0,0,1] op_sel_hi:[1,0,1]
	v_pk_fma_f32 v[84:85], v[84:85], s[72:73], v[136:137] op_sel:[0,0,1] op_sel_hi:[1,0,1]
	v_pk_fma_f32 v[86:87], v[86:87], s[72:73], v[136:137] op_sel:[0,0,1] op_sel_hi:[1,0,1]
	v_pk_fma_f32 v[88:89], v[88:89], s[72:73], v[136:137] op_sel:[0,0,1] op_sel_hi:[1,0,1]
	s_waitcnt lgkmcnt(0)
	v_mfma_f32_32x32x16_bf16 v[16:31], v[178:181], v[174:177], v[16:31]
	ds_read_b64_tr_b16 v[174:175], v160 offset:0x600
	ds_read_b64_tr_b16 v[176:177], v160 offset:0xe00
	v_pk_fma_f32 v[90:91], v[90:91], s[72:73], v[136:137] op_sel:[0,0,1] op_sel_hi:[1,0,1]
	v_pk_fma_f32 v[92:93], v[92:93], s[72:73], v[136:137] op_sel:[0,0,1] op_sel_hi:[1,0,1]
	v_pk_fma_f32 v[94:95], v[94:95], s[72:73], v[136:137] op_sel:[0,0,1] op_sel_hi:[1,0,1]
	v_exp_f32_e32 v127, v80
	v_mfma_f32_32x32x16_bf16 v[16:31], v[144:147], v[182:185], v[16:31]
	ds_read_b64_tr_b16 v[182:183], v160 offset:0x1600
	ds_read_b64_tr_b16 v[184:185], v160 offset:0x1e00
	v_exp_f32_e32 v129, v81
	v_exp_f32_e32 v125, v82
	v_exp_f32_e32 v128, v83
	v_mfma_f32_32x32x16_bf16 v[16:31], v[166:169], v[186:189], v[16:31]
	ds_read_b64_tr_b16 v[186:187], v160 offset:0x2600
	ds_read_b64_tr_b16 v[188:189], v160 offset:0x2e00
	v_exp_f32_e32 v123, v84
	v_exp_f32_e32 v126, v85
	v_exp_f32_e32 v122, v86
	v_mfma_f32_32x32x16_bf16 v[16:31], v[170:173], v[212:215], v[16:31]
	ds_read_b64_tr_b16 v[212:213], v160 offset:0x3600
	ds_read_b64_tr_b16 v[214:215], v160 offset:0x3e00
	v_exp_f32_e32 v124, v87
	v_exp_f32_e32 v119, v88
	v_exp_f32_e32 v121, v89
	s_waitcnt lgkmcnt(0)
	v_mfma_f32_32x32x16_bf16 v[0:15], v[178:181], v[174:177], v[0:15]
	s_barrier
	s_waitcnt vmcnt(0)
	s_waitcnt vmcnt(3)
	ds_write_b128 v163, v[240:243]
	s_waitcnt vmcnt(1)
	ds_write_b128 v164, v[206:209]
	ds_write_b128 v161, v[244:247] offset:32768
	s_waitcnt vmcnt(0)
	ds_write_b128 v162, v[248:251] offset:32768
	v_exp_f32_e32 v117, v90
	v_exp_f32_e32 v120, v91
	v_exp_f32_e32 v115, v92
	v_mfma_f32_32x32x16_bf16 v[0:15], v[144:147], v[182:185], v[0:15]
	v_exp_f32_e32 v118, v93
	v_exp_f32_e32 v114, v94
	v_exp_f32_e32 v116, v95
	v_mfma_f32_32x32x16_bf16 v[0:15], v[166:169], v[186:189], v[0:15]
	v_mfma_f32_32x32x16_bf16 v[0:15], v[170:173], v[212:215], v[0:15]
	v_cmp_gt_f32_e32 vcc, 1.0, v138
	s_cbranch_vccz .LBB0_284
	s_and_saveexec_b64 s[2:3], s[6:7]
	ds_write_b32 v157, v138 offset:128
	s_or_b64 exec, exec, s[2:3]
	s_waitcnt lgkmcnt(0)
	ds_read_b128 v[240:243], v158 offset:224
	ds_read_b128 v[244:247], v158 offset:192
	ds_read_b128 v[248:251], v158 offset:160
	ds_read_b128 v[206:209], v158 offset:128
	s_waitcnt lgkmcnt(3)
	v_pk_mul_f32 v[62:63], v[62:63], v[242:243]
	s_waitcnt lgkmcnt(2)
	v_pk_mul_f32 v[58:59], v[58:59], v[246:247]
	s_waitcnt lgkmcnt(1)
	v_pk_mul_f32 v[54:55], v[54:55], v[250:251]
	s_waitcnt lgkmcnt(0)
	v_pk_mul_f32 v[50:51], v[50:51], v[208:209]
	v_pk_mul_f32 v[60:61], v[60:61], v[240:241]
	v_pk_mul_f32 v[56:57], v[56:57], v[244:245]
	v_pk_mul_f32 v[52:53], v[52:53], v[248:249]
	v_pk_mul_f32 v[48:49], v[48:49], v[206:207]
	v_pk_mul_f32 v[46:47], v[46:47], v[242:243]
	v_pk_mul_f32 v[42:43], v[42:43], v[246:247]
	v_pk_mul_f32 v[38:39], v[38:39], v[250:251]
	v_pk_mul_f32 v[34:35], v[34:35], v[208:209]
	v_pk_mul_f32 v[44:45], v[44:45], v[240:241]
	v_pk_mul_f32 v[40:41], v[40:41], v[244:245]
	v_pk_mul_f32 v[36:37], v[36:37], v[248:249]
	v_pk_mul_f32 v[32:33], v[32:33], v[206:207]
	v_pk_mul_f32 v[30:31], v[30:31], v[242:243]
	v_pk_mul_f32 v[26:27], v[26:27], v[246:247]
	v_pk_mul_f32 v[22:23], v[22:23], v[250:251]
	v_pk_mul_f32 v[18:19], v[18:19], v[208:209]
	v_pk_mul_f32 v[28:29], v[28:29], v[240:241]
	v_pk_mul_f32 v[24:25], v[24:25], v[244:245]
	v_pk_mul_f32 v[20:21], v[20:21], v[248:249]
	v_pk_mul_f32 v[16:17], v[16:17], v[206:207]
	v_pk_mul_f32 v[14:15], v[14:15], v[242:243]
	v_pk_mul_f32 v[10:11], v[10:11], v[246:247]
	v_pk_mul_f32 v[6:7], v[6:7], v[250:251]
	v_pk_mul_f32 v[2:3], v[2:3], v[208:209]
	v_pk_mul_f32 v[12:13], v[12:13], v[240:241]
	v_pk_mul_f32 v[8:9], v[8:9], v[244:245]
	v_pk_mul_f32 v[4:5], v[4:5], v[248:249]
	v_pk_mul_f32 v[0:1], v[0:1], v[206:207]
; __device__ __forceinline__ void partialSM(f32x16& p0, f32x16& p1, float& m_reg, float& mn, float& alpha) {
;     constexpr float C = SCALE * 1.4426950408889634f;
;     float pmax = p0[0];
; #pragma unroll
;     for (int r = 1; r < 16; ++r) pmax = fmaxf(pmax, p0[r]);
; #pragma unroll
;     for (int r = 0; r < 16; ++r) pmax = fmaxf(pmax, p1[r]);
;     { auto rr = __builtin_amdgcn_permlane32_swap(__float_as_uint(pmax), __float_as_uint(pmax), false, false);
;       pmax = fmaxf(__uint_as_float(rr[0]), __uint_as_float(rr[1])); }
;     if (__builtin_expect(__all(pmax - m_reg <= THR / SCALE), 1)) { mn = m_reg; alpha = 1.f; }
;     else { mn = fmaxf(m_reg, pmax); alpha = __builtin_amdgcn_exp2f((m_reg - mn) * C); m_reg = mn; }
;     const float mnC = -mn * C;
; #pragma unroll
;     for (int r = 0; r < 16; ++r) p0[r] = fmaf(p0[r], C, mnC);
; #pragma unroll
;     for (int r = 0; r < 16; ++r) p1[r] = fmaf(p1[r], C, mnC);
; #pragma unroll
;     for (int r = 0; r < 16; ++r) p0[r] = __builtin_amdgcn_exp2f(p0[r]);
; }
; __device__ __forceinline__ void finishSM(f32x16& p0, f32x16& p1, float alpha, float& l_reg, bf16x8& pa0, bf16x8& pa1, bf16x8& pa2, bf16x8& pa3) {
; #pragma unroll
;     for (int r = 0; r < 16; ++r) p1[r] = __builtin_amdgcn_exp2f(p1[r]);
;     float ps = 0;
; #pragma unroll
;     for (int r = 0; r < 16; ++r) ps += p0[r];
; #pragma unroll
;     for (int r = 0; r < 16; ++r) ps += p1[r];
;     { auto rr = __builtin_amdgcn_permlane32_swap(__float_as_uint(ps), __float_as_uint(ps), false, false);
;       ps = __uint_as_float(rr[0]) + __uint_as_float(rr[1]); }
;     l_reg = l_reg * alpha + ps;
;     ...
;     PK4(p0, 0, pa0); PK4(p0, 8, pa1); PK4(p1, 0, pa2); PK4(p1, 8, pa3);
;     ...
; }
; __device__ __forceinline__ void qkt(f32x16& p0, f32x16& p1, const char* Ks, const bf16x8* qr, int r32, int hi, int comp) {
;     p0 = f32x16{}; p1 = f32x16{};
; #pragma unroll
;     for (int d0 = 0; d0 < 4; ++d0) { const int cb = (comp * 64 + d0 * 16 + hi * 8) * 2;
;         const bf16x8 b0 = *reinterpret_cast<const bf16x8*>(Ks + KSWZ(r32, cb));
;         const bf16x8 b1 = *reinterpret_cast<const bf16x8*>(Ks + KSWZ(32 + r32, cb));
;         p0 = __builtin_amdgcn_mfma_f32_32x32x16_bf16(b0, qr[d0], p0, 0, 0, 0);
;         p1 = __builtin_amdgcn_mfma_f32_32x32x16_bf16(b1, qr[d0], p1, 0, 0, 0); }
; }
.LBB0_284:
	v_fmamk_f32 v167, v64, 0x3e38aa3b, v137
	v_fmamk_f32 v168, v65, 0x3e38aa3b, v137
	v_fmamk_f32 v169, v66, 0x3e38aa3b, v137
	v_fmamk_f32 v170, v67, 0x3e38aa3b, v137
	v_fmamk_f32 v171, v68, 0x3e38aa3b, v137
	v_fmamk_f32 v144, v69, 0x3e38aa3b, v137
	v_fmamk_f32 v145, v70, 0x3e38aa3b, v137
	v_fmamk_f32 v146, v71, 0x3e38aa3b, v137
	v_fmamk_f32 v147, v72, 0x3e38aa3b, v137
	v_fmamk_f32 v148, v73, 0x3e38aa3b, v137
	v_fmamk_f32 v149, v74, 0x3e38aa3b, v137
	v_fmamk_f32 v166, v75, 0x3e38aa3b, v137
	v_fmamk_f32 v139, v76, 0x3e38aa3b, v137
	v_fmamk_f32 v172, v77, 0x3e38aa3b, v137
	v_fmamk_f32 v173, v78, 0x3e38aa3b, v137
	v_fmac_f32_e32 v137, 0x3e38aa3b, v79
	s_waitcnt lgkmcnt(0)
	s_barrier
	ds_read_b128 v[64:67], v140 offset:32768
	ds_read_b128 v[68:71], v140 offset:40960
	ds_read_b128 v[174:177], v143 offset:32768
	ds_read_b128 v[178:181], v143 offset:40960
	v_exp_f32_e32 v185, v139
	v_add_f32_e32 v139, 0, v127
	s_waitcnt lgkmcnt(3)
	v_mfma_f32_32x32x16_bf16 v[80:95], v[64:67], v[110:113], 0
	v_add_f32_e32 v139, v129, v139
	v_add_f32_e32 v139, v125, v139
	v_add_f32_e32 v139, v128, v139
	v_add_f32_e32 v139, v123, v139
	v_add_f32_e32 v139, v126, v139
	v_add_f32_e32 v139, v122, v139
	v_add_f32_e32 v139, v124, v139
	s_waitcnt lgkmcnt(2)
	v_mfma_f32_32x32x16_bf16 v[64:79], v[68:71], v[110:113], 0
	v_add_f32_e32 v139, v119, v139
	v_add_f32_e32 v139, v121, v139
	v_add_f32_e32 v139, v117, v139
	v_add_f32_e32 v139, v120, v139
	v_add_f32_e32 v139, v115, v139
	v_add_f32_e32 v139, v118, v139
	v_add_f32_e32 v139, v114, v139
	s_waitcnt lgkmcnt(1)
	v_mfma_f32_32x32x16_bf16 v[80:95], v[174:177], v[106:109], v[80:95]
	v_add_f32_e32 v139, v116, v139
	v_exp_f32_e32 v145, v145
	v_exp_f32_e32 v182, v148
	v_exp_f32_e32 v183, v149
	v_exp_f32_e32 v184, v166
	v_exp_f32_e32 v186, v172
	v_exp_f32_e32 v187, v173
	s_waitcnt lgkmcnt(0)
	v_mfma_f32_32x32x16_bf16 v[64:79], v[178:181], v[106:109], v[64:79]
	ds_read_b128 v[174:177], v142 offset:32768
	ds_read_b128 v[178:181], v142 offset:40960
	v_exp_f32_e32 v137, v137
	s_waitcnt lgkmcnt(1)
	v_mfma_f32_32x32x16_bf16 v[80:95], v[174:177], v[102:105], v[80:95]
	s_waitcnt lgkmcnt(0)
	v_mfma_f32_32x32x16_bf16 v[64:79], v[178:181], v[102:105], v[64:79]
	ds_read_b128 v[174:177], v141 offset:32768
	ds_read_b128 v[178:181], v141 offset:40960
	s_waitcnt lgkmcnt(1)
	v_mfma_f32_32x32x16_bf16 v[80:95], v[174:177], v[98:101], v[80:95]
	v_exp_f32_e32 v174, v167
	v_exp_f32_e32 v175, v168
	v_exp_f32_e32 v176, v169
	v_exp_f32_e32 v177, v170
	v_add_f32_e32 v139, v174, v139
	v_add_f32_e32 v139, v175, v139
	v_add_f32_e32 v139, v176, v139
	s_waitcnt lgkmcnt(0)
	v_mfma_f32_32x32x16_bf16 v[64:79], v[178:181], v[98:101], v[64:79]
	v_exp_f32_e32 v178, v171
	v_exp_f32_e32 v179, v144
	v_exp_f32_e32 v180, v146
	v_add_f32_e32 v139, v177, v139
	v_exp_f32_e32 v181, v147
	v_add_f32_e32 v139, v178, v139
	v_add_f32_e32 v139, v179, v139
	v_add_f32_e32 v139, v145, v139
	v_add_f32_e32 v139, v180, v139
	v_add_f32_e32 v139, v181, v139
	v_add_f32_e32 v139, v182, v139
	v_add_f32_e32 v139, v183, v139
	v_add_f32_e32 v139, v184, v139
	v_add_f32_e32 v139, v185, v139
	v_add_f32_e32 v139, v186, v139
	v_add_f32_e32 v139, v187, v139
	v_add_f32_e32 v139, v137, v139
	v_mov_b32_e32 v144, v139
	s_nop 1
	v_permlane32_swap_b32_e32 v139, v144
	v_cvt_pk_bf16_f32 v146, v127, v129
	v_cvt_pk_bf16_f32 v147, v125, v128
	v_cvt_pk_bf16_f32 v148, v123, v126
	v_cvt_pk_bf16_f32 v149, v122, v124
	v_cvt_pk_bf16_f32 v166, v119, v121
	v_cvt_pk_bf16_f32 v167, v117, v120
	v_cvt_pk_bf16_f32 v168, v115, v118
	v_cvt_pk_bf16_f32 v169, v114, v116
	v_cvt_pk_bf16_f32 v170, v174, v175
	v_cvt_pk_bf16_f32 v171, v176, v177
	v_cvt_pk_bf16_f32 v172, v178, v179
	v_cvt_pk_bf16_f32 v173, v145, v180
	v_cvt_pk_bf16_f32 v174, v181, v182
	v_cvt_pk_bf16_f32 v175, v183, v184
	v_cvt_pk_bf16_f32 v176, v185, v186
	v_cvt_pk_bf16_f32 v177, v187, v137
	s_nop 0
	v_permlane32_swap_b32_e32 v146, v148
	v_permlane32_swap_b32_e32 v147, v149
	v_permlane32_swap_b32_e32 v166, v168
	v_permlane32_swap_b32_e32 v167, v169
	v_permlane32_swap_b32_e32 v170, v172
	v_permlane32_swap_b32_e32 v171, v173
	v_permlane32_swap_b32_e32 v174, v176
	v_permlane32_swap_b32_e32 v175, v177
	v_add_u32_e32 v118, 0x20000, v96
	v_add_u32_e32 v122, 0x30000, v96
	global_load_dwordx4 v[114:117], v118, s[58:59]
	s_nop 0
	global_load_dwordx4 v[118:121], v118, s[28:29]
	s_nop 0
	global_load_dwordx4 v[126:129], v122, s[58:59]
	s_nop 0
	global_load_dwordx4 v[122:125], v122, s[28:29]
	ds_read_b64_tr_b16 v[178:179], v159 offset:0
	ds_read_b64_tr_b16 v[180:181], v159 offset:0x800
	ds_read_b64_tr_b16 v[182:183], v159 offset:0x1000
	ds_read_b64_tr_b16 v[184:185], v159 offset:0x1800
	ds_read_b64_tr_b16 v[186:187], v159 offset:0x2000
	ds_read_b64_tr_b16 v[188:189], v159 offset:0x2800
	ds_read_b64_tr_b16 v[212:213], v159 offset:0x3000
	ds_read_b64_tr_b16 v[214:215], v159 offset:0x3800
	s_waitcnt lgkmcnt(0)
	s_nop 0
	v_mfma_f32_32x32x16_bf16 v[48:63], v[146:149], v[178:181], v[48:63]
	ds_read_b64_tr_b16 v[178:179], v159 offset:0x200
	ds_read_b64_tr_b16 v[180:181], v159 offset:0xa00
	v_max_f32_e32 v255, v81, v81
	v_max_f32_e32 v210, v80, v80
	v_max3_f32 v145, v64, v65, v66
	v_max_f32_e32 v255, v210, v255
	v_max3_f32 v145, v145, v67, v68
	v_mfma_f32_32x32x16_bf16 v[48:63], v[166:169], v[182:185], v[48:63]
	ds_read_b64_tr_b16 v[182:183], v159 offset:0x1200
	ds_read_b64_tr_b16 v[184:185], v159 offset:0x1a00
	v_max3_f32 v255, v255, v82, v83
	v_max3_f32 v145, v145, v69, v70
	v_max3_f32 v255, v255, v84, v85
	v_max3_f32 v145, v145, v71, v72
	v_max3_f32 v255, v255, v86, v87
	v_mfma_f32_32x32x16_bf16 v[48:63], v[170:173], v[186:189], v[48:63]
	ds_read_b64_tr_b16 v[186:187], v159 offset:0x2200
	ds_read_b64_tr_b16 v[188:189], v159 offset:0x2a00
	v_max3_f32 v145, v145, v73, v74
	v_max3_f32 v255, v255, v88, v89
	v_max3_f32 v145, v145, v75, v76
	v_max3_f32 v255, v255, v90, v91
	v_max3_f32 v145, v145, v77, v78
	v_mfma_f32_32x32x16_bf16 v[48:63], v[174:177], v[212:215], v[48:63]
	ds_read_b64_tr_b16 v[212:213], v159 offset:0x3200
	ds_read_b64_tr_b16 v[214:215], v159 offset:0x3a00
	v_max3_f32 v255, v255, v92, v93
	v_max_f32_e32 v145, v79, v145
	v_max3_f32 v255, v255, v94, v95
	v_max_f32_e32 v255, v255, v145
	v_mov_b32_e32 v210, v255
	s_nop 1
	v_permlane32_swap_b32_e32 v255, v210
	s_waitcnt lgkmcnt(0)
; __device__ __forceinline__ void partialSM(f32x16& p0, f32x16& p1, float& m_reg, float& mn, float& alpha) {
;     ...
;     { auto rr = __builtin_amdgcn_permlane32_swap(__float_as_uint(pmax), __float_as_uint(pmax), false, false);
;       pmax = fmaxf(__uint_as_float(rr[0]), __uint_as_float(rr[1])); }
;     if (__builtin_expect(__all(pmax - m_reg <= THR / SCALE), 1)) { mn = m_reg; alpha = 1.f; }
;     else { mn = fmaxf(m_reg, pmax); alpha = __builtin_amdgcn_exp2f((m_reg - mn) * C); m_reg = mn; }
;     const float mnC = -mn * C;
; #pragma unroll
;     for (int r = 0; r < 16; ++r) p0[r] = fmaf(p0[r], C, mnC);
; #pragma unroll
;     for (int r = 0; r < 16; ++r) p1[r] = fmaf(p1[r], C, mnC);
; #pragma unroll
;     for (int r = 0; r < 16; ++r) p0[r] = __builtin_amdgcn_exp2f(p0[r]);
; }
	v_mfma_f32_32x32x16_bf16 v[32:47], v[146:149], v[178:181], v[32:47]
	ds_read_b64_tr_b16 v[178:179], v159 offset:0x400
	ds_read_b64_tr_b16 v[180:181], v159 offset:0xc00
	v_max_f32_e32 v210, v210, v210
	v_max_f32_e32 v255, v255, v255
	v_max_f32_e32 v255, v255, v210
	v_sub_f32_e32 v210, v255, v134
	v_cmp_ge_f32_e32 vcc, s65, v210
	v_mfma_f32_32x32x16_bf16 v[32:47], v[166:169], v[182:185], v[32:47]
	ds_read_b64_tr_b16 v[182:183], v159 offset:0x1400
	ds_read_b64_tr_b16 v[184:185], v159 offset:0x1c00
	v_max_f32_e32 v210, v134, v134
	v_max_f32_e32 v210, v210, v255
	v_sub_f32_e32 v255, v134, v210
	v_mul_f32_e32 v255, 0x3e38aa3b, v255
	v_exp_f32_e32 v255, v255
	v_mfma_f32_32x32x16_bf16 v[32:47], v[170:173], v[186:189], v[32:47]
	ds_read_b64_tr_b16 v[186:187], v159 offset:0x2400
	ds_read_b64_tr_b16 v[188:189], v159 offset:0x2c00
	s_cmp_eq_u64 vcc, exec
	s_cselect_b64 s[8:9], -1, 0
	v_cndmask_b32_e64 v255, v255, 1.0, s[8:9]
	v_cndmask_b32_e64 v134, v210, v134, s[8:9]
	v_mul_f32_e32 v210, 0xbe38aa3b, v134
	v_mfma_f32_32x32x16_bf16 v[32:47], v[174:177], v[212:215], v[32:47]
	ds_read_b64_tr_b16 v[212:213], v159 offset:0x3400
	ds_read_b64_tr_b16 v[214:215], v159 offset:0x3c00
	v_pk_fma_f32 v[80:81], v[80:81], s[72:73], v[210:211] op_sel_hi:[1,0,0]
	v_pk_fma_f32 v[82:83], v[82:83], s[72:73], v[210:211] op_sel_hi:[1,0,0]
	v_pk_fma_f32 v[84:85], v[84:85], s[72:73], v[210:211] op_sel_hi:[1,0,0]
	v_pk_fma_f32 v[86:87], v[86:87], s[72:73], v[210:211] op_sel_hi:[1,0,0]
	v_pk_fma_f32 v[88:89], v[88:89], s[72:73], v[210:211] op_sel_hi:[1,0,0]
	s_waitcnt lgkmcnt(0)
	v_mfma_f32_32x32x16_bf16 v[16:31], v[146:149], v[178:181], v[16:31]
	ds_read_b64_tr_b16 v[178:179], v159 offset:0x600
	ds_read_b64_tr_b16 v[180:181], v159 offset:0xe00
	v_pk_fma_f32 v[90:91], v[90:91], s[72:73], v[210:211] op_sel_hi:[1,0,0]
	v_pk_fma_f32 v[92:93], v[92:93], s[72:73], v[210:211] op_sel_hi:[1,0,0]
	v_pk_fma_f32 v[94:95], v[94:95], s[72:73], v[210:211] op_sel_hi:[1,0,0]
	v_exp_f32_e32 v240, v80
	v_mfma_f32_32x32x16_bf16 v[16:31], v[166:169], v[182:185], v[16:31]
	ds_read_b64_tr_b16 v[182:183], v159 offset:0x1600
	ds_read_b64_tr_b16 v[184:185], v159 offset:0x1e00
	v_exp_f32_e32 v241, v81
	v_exp_f32_e32 v242, v82
	v_exp_f32_e32 v243, v83
	v_mfma_f32_32x32x16_bf16 v[16:31], v[170:173], v[186:189], v[16:31]
	ds_read_b64_tr_b16 v[186:187], v159 offset:0x2600
	ds_read_b64_tr_b16 v[188:189], v159 offset:0x2e00
	v_exp_f32_e32 v244, v84
	v_exp_f32_e32 v245, v85
	v_exp_f32_e32 v246, v86
	v_mfma_f32_32x32x16_bf16 v[16:31], v[174:177], v[212:215], v[16:31]
	ds_read_b64_tr_b16 v[212:213], v159 offset:0x3600
	ds_read_b64_tr_b16 v[214:215], v159 offset:0x3e00
	v_exp_f32_e32 v247, v87
	v_exp_f32_e32 v248, v88
	v_exp_f32_e32 v249, v89
	s_waitcnt lgkmcnt(0)
	v_mfma_f32_32x32x16_bf16 v[0:15], v[146:149], v[178:181], v[0:15]
	s_barrier
	s_waitcnt vmcnt(0)
	s_waitcnt vmcnt(3)
	ds_write_b128 v163, v[114:117] offset:16384
	s_waitcnt vmcnt(1)
	ds_write_b128 v164, v[126:129] offset:16384
	ds_write_b128 v161, v[118:121] offset:49152
	s_waitcnt vmcnt(0)
	ds_write_b128 v162, v[122:125] offset:49152
	v_exp_f32_e32 v250, v90
	v_exp_f32_e32 v251, v91
	v_exp_f32_e32 v206, v92
	v_mfma_f32_32x32x16_bf16 v[0:15], v[166:169], v[182:185], v[0:15]
	v_exp_f32_e32 v207, v93
	v_exp_f32_e32 v208, v94
	v_exp_f32_e32 v209, v95
	v_mfma_f32_32x32x16_bf16 v[0:15], v[170:173], v[186:189], v[0:15]
	v_mfma_f32_32x32x16_bf16 v[0:15], v[174:177], v[212:215], v[0:15]
	v_mov_b32_e32 v137, v255
	v_cmp_gt_f32_e32 vcc, 1.0, v137
	s_cbranch_vccz .LBB0_288
	s_and_saveexec_b64 s[2:3], s[6:7]
	ds_write_b32 v157, v137 offset:128
	s_or_b64 exec, exec, s[2:3]
	s_waitcnt lgkmcnt(0)
	ds_read_b128 v[114:117], v158 offset:224
	ds_read_b128 v[118:121], v158 offset:192
	ds_read_b128 v[122:125], v158 offset:160
	ds_read_b128 v[126:129], v158 offset:128
	s_waitcnt lgkmcnt(3)
	v_pk_mul_f32 v[62:63], v[62:63], v[116:117]
	s_waitcnt lgkmcnt(2)
	v_pk_mul_f32 v[58:59], v[58:59], v[120:121]
	s_waitcnt lgkmcnt(1)
	v_pk_mul_f32 v[54:55], v[54:55], v[124:125]
	s_waitcnt lgkmcnt(0)
	v_pk_mul_f32 v[50:51], v[50:51], v[128:129]
	v_pk_mul_f32 v[60:61], v[60:61], v[114:115]
	v_pk_mul_f32 v[56:57], v[56:57], v[118:119]
	v_pk_mul_f32 v[52:53], v[52:53], v[122:123]
	v_pk_mul_f32 v[48:49], v[48:49], v[126:127]
	v_pk_mul_f32 v[46:47], v[46:47], v[116:117]
	v_pk_mul_f32 v[42:43], v[42:43], v[120:121]
	v_pk_mul_f32 v[38:39], v[38:39], v[124:125]
	v_pk_mul_f32 v[34:35], v[34:35], v[128:129]
	v_pk_mul_f32 v[44:45], v[44:45], v[114:115]
	v_pk_mul_f32 v[40:41], v[40:41], v[118:119]
	v_pk_mul_f32 v[36:37], v[36:37], v[122:123]
	v_pk_mul_f32 v[32:33], v[32:33], v[126:127]
	v_pk_mul_f32 v[30:31], v[30:31], v[116:117]
	v_pk_mul_f32 v[26:27], v[26:27], v[120:121]
	v_pk_mul_f32 v[22:23], v[22:23], v[124:125]
	v_pk_mul_f32 v[18:19], v[18:19], v[128:129]
	v_pk_mul_f32 v[28:29], v[28:29], v[114:115]
	v_pk_mul_f32 v[24:25], v[24:25], v[118:119]
	v_pk_mul_f32 v[20:21], v[20:21], v[122:123]
	v_pk_mul_f32 v[16:17], v[16:17], v[126:127]
	v_pk_mul_f32 v[14:15], v[14:15], v[116:117]
	v_pk_mul_f32 v[10:11], v[10:11], v[120:121]
	v_pk_mul_f32 v[6:7], v[6:7], v[124:125]
	v_pk_mul_f32 v[2:3], v[2:3], v[128:129]
	v_pk_mul_f32 v[12:13], v[12:13], v[114:115]
	v_pk_mul_f32 v[8:9], v[8:9], v[118:119]
	v_pk_mul_f32 v[4:5], v[4:5], v[122:123]
	v_pk_mul_f32 v[0:1], v[0:1], v[126:127]
